# differential mixer unit epilogue: lambda and the eight group-norm gain loads issued at the top with one wait (were five serialized round trips)
# baseline (speedup 1.0000x reference)
.LBB0_733:
	v_lshlrev_b64 v[180:181], 11, v[192:193]
	v_lshl_add_u64 v[180:181], s[0:1], 0, v[180:181]
	s_add_u32 s0, s0, s4
	s_addc_u32 s1, s1, s5
	v_mov_b32_e32 v178, s0
	s_mov_b32 s0, 0x300000
	v_add_co_u32_e32 v178, vcc, s0, v178
	v_mov_b32_e32 v179, s1
	v_lshlrev_b32_e32 v177, 2, v191
	v_addc_co_u32_e32 v179, vcc, 0, v179, vcc
	flat_load_dwordx2 v[178:179], v[178:179]
	global_load_dwordx4 v[144:147], v177, s[2:3]
	global_load_dwordx4 v[148:151], v177, s[2:3] offset:32
	global_load_dwordx4 v[152:155], v177, s[2:3] offset:64
	global_load_dwordx4 v[156:159], v177, s[2:3] offset:96
	global_load_dwordx4 v[160:163], v177, s[2:3] offset:128
	global_load_dwordx4 v[164:167], v177, s[2:3] offset:160
	global_load_dwordx4 v[168:171], v177, s[2:3] offset:192
	global_load_dwordx4 v[172:175], v177, s[2:3] offset:224
	v_mov_b32_e32 v48, v98
	s_nop 1
	v_permlane32_swap_b32_e32 v98, v48
	v_add_f32_e32 v48, v98, v48
	v_div_scale_f32 v49, s[6:7], v48, v48, 1.0
	v_rcp_f32_e32 v50, v49
	v_lshlrev_b32_e32 v184, 1, v190
	v_fma_f32 v51, -v49, v50, 1.0
	v_fmac_f32_e32 v50, v51, v50
	v_div_scale_f32 v51, vcc, 1.0, v48, 1.0
	v_mul_f32_e32 v52, v51, v50
	v_fma_f32 v53, -v49, v52, v51
	v_fmac_f32_e32 v52, v53, v50
	v_fma_f32 v49, -v49, v52, v51
	v_div_fmas_f32 v49, v49, v50, v52
	v_div_fixup_f32 v56, v49, v48, 1.0
	v_mov_b32_e32 v48, v96
	s_nop 1
	v_permlane32_swap_b32_e32 v96, v48
	v_add_f32_e32 v48, v96, v48
	v_div_scale_f32 v49, s[6:7], v48, v48, 1.0
	v_rcp_f32_e32 v50, v49
	s_nop 0
	v_fma_f32 v51, -v49, v50, 1.0
	v_fmac_f32_e32 v50, v51, v50
	v_div_scale_f32 v51, vcc, 1.0, v48, 1.0
	v_mul_f32_e32 v52, v51, v50
	v_fma_f32 v53, -v49, v52, v51
	v_fmac_f32_e32 v52, v53, v50
	v_fma_f32 v49, -v49, v52, v51
	v_div_fmas_f32 v49, v49, v50, v52
	v_div_fixup_f32 v52, v49, v48, 1.0
	s_lshl_b32 s60, s12, 1
	s_mov_b32 s0, 0xf800000
	s_add_i32 s11, s11, s42
	s_cmpk_gt_i32 s11, 0x1ff
	s_waitcnt vmcnt(0) lgkmcnt(0)
	v_mul_f32_e32 v60, v178, v52
	v_pk_mul_f32 v[46:47], v[46:47], v[60:61] op_sel_hi:[1,0]
	v_sub_f32_e32 v61, 1.0, v179
	v_pk_fma_f32 v[14:15], v[14:15], v[56:57], v[46:47] op_sel_hi:[1,0,1] neg_lo:[0,0,1] neg_hi:[0,0,1]
	v_lshl_add_u64 v[46:47], v[180:181], 0, s[60:61]
	v_lshlrev_b32_e32 v57, 2, v191
	v_lshl_add_u64 v[58:59], v[46:47], 0, v[184:185]
	v_pk_mul_f32 v[62:63], v[70:71], v[60:61] op_sel_hi:[1,0]
	v_pk_mul_f32 v[32:33], v[32:33], v[60:61] op_sel_hi:[1,0]
	v_pk_fma_f32 v[22:23], v[22:23], v[56:57], v[62:63] op_sel_hi:[1,0,1] neg_lo:[0,0,1] neg_hi:[0,0,1]
	v_pk_mul_f32 v[62:63], v[68:69], v[60:61] op_sel_hi:[1,0]
	v_pk_mul_f32 v[34:35], v[34:35], v[60:61] op_sel_hi:[1,0]
	v_pk_fma_f32 v[20:21], v[20:21], v[56:57], v[62:63] op_sel_hi:[1,0,1] neg_lo:[0,0,1] neg_hi:[0,0,1]
	v_pk_mul_f32 v[62:63], v[66:67], v[60:61] op_sel_hi:[1,0]
	v_pk_fma_f32 v[0:1], v[0:1], v[56:57], v[32:33] op_sel_hi:[1,0,1] neg_lo:[0,0,1] neg_hi:[0,0,1]
	v_pk_fma_f32 v[18:19], v[18:19], v[56:57], v[62:63] op_sel_hi:[1,0,1] neg_lo:[0,0,1] neg_hi:[0,0,1]
	v_pk_mul_f32 v[62:63], v[64:65], v[60:61] op_sel_hi:[1,0]
	v_mul_f32_e32 v64, v19, v19
	v_pk_fma_f32 v[16:17], v[16:17], v[56:57], v[62:63] op_sel_hi:[1,0,1] neg_lo:[0,0,1] neg_hi:[0,0,1]
	v_pk_fma_f32 v[2:3], v[2:3], v[56:57], v[34:35] op_sel_hi:[1,0,1] neg_lo:[0,0,1] neg_hi:[0,0,1]
	v_mul_f32_e32 v62, v17, v17
	v_pk_fma_f32 v[62:63], v[16:17], v[16:17], v[62:63] op_sel_hi:[1,1,0]
	v_mul_f32_e32 v34, v1, v1
	v_pk_fma_f32 v[62:63], v[18:19], v[18:19], v[62:63]
	v_pk_mul_f32 v[36:37], v[36:37], v[60:61] op_sel_hi:[1,0]
	v_pk_add_f32 v[62:63], v[64:65], v[62:63] op_sel_hi:[0,1]
	v_pk_fma_f32 v[62:63], v[20:21], v[20:21], v[62:63]
	v_mul_f32_e32 v64, v21, v21
	v_pk_add_f32 v[62:63], v[64:65], v[62:63] op_sel_hi:[0,1]
	v_pk_fma_f32 v[62:63], v[22:23], v[22:23], v[62:63]
	v_mul_f32_e32 v64, v23, v23
	v_pk_add_f32 v[62:63], v[64:65], v[62:63] op_sel_hi:[0,1]
	v_pk_mul_f32 v[64:65], v[78:79], v[60:61] op_sel_hi:[1,0]
	v_pk_fma_f32 v[4:5], v[4:5], v[56:57], v[36:37] op_sel_hi:[1,0,1] neg_lo:[0,0,1] neg_hi:[0,0,1]
	v_pk_fma_f32 v[30:31], v[30:31], v[56:57], v[64:65] op_sel_hi:[1,0,1] neg_lo:[0,0,1] neg_hi:[0,0,1]
	v_pk_mul_f32 v[64:65], v[76:77], v[60:61] op_sel_hi:[1,0]
	v_pk_mul_f32 v[38:39], v[38:39], v[60:61] op_sel_hi:[1,0]
	v_pk_fma_f32 v[28:29], v[28:29], v[56:57], v[64:65] op_sel_hi:[1,0,1] neg_lo:[0,0,1] neg_hi:[0,0,1]
	v_pk_mul_f32 v[64:65], v[74:75], v[60:61] op_sel_hi:[1,0]
	v_pk_fma_f32 v[6:7], v[6:7], v[56:57], v[38:39] op_sel_hi:[1,0,1] neg_lo:[0,0,1] neg_hi:[0,0,1]
	v_pk_fma_f32 v[26:27], v[26:27], v[56:57], v[64:65] op_sel_hi:[1,0,1] neg_lo:[0,0,1] neg_hi:[0,0,1]
	v_pk_mul_f32 v[64:65], v[72:73], v[60:61] op_sel_hi:[1,0]
	v_lshl_add_u64 v[54:55], v[58:59], 0, s[20:21]
	v_pk_fma_f32 v[24:25], v[24:25], v[56:57], v[64:65] op_sel_hi:[1,0,1] neg_lo:[0,0,1] neg_hi:[0,0,1]
	s_nop 0
	v_pk_fma_f32 v[62:63], v[24:25], v[24:25], v[62:63]
	v_mul_f32_e32 v64, v25, v25
	v_pk_add_f32 v[62:63], v[64:65], v[62:63] op_sel_hi:[0,1]
	v_pk_fma_f32 v[62:63], v[26:27], v[26:27], v[62:63]
	v_mul_f32_e32 v64, v27, v27
	v_pk_add_f32 v[62:63], v[64:65], v[62:63] op_sel_hi:[0,1]
	v_pk_fma_f32 v[62:63], v[28:29], v[28:29], v[62:63]
	v_mul_f32_e32 v64, v29, v29
	v_pk_add_f32 v[62:63], v[64:65], v[62:63] op_sel_hi:[0,1]
	v_pk_fma_f32 v[62:63], v[30:31], v[30:31], v[62:63]
	v_mul_f32_e32 v64, v31, v31
	v_pk_add_f32 v[62:63], v[64:65], v[62:63] op_sel_hi:[0,1]
	v_pk_fma_f32 v[32:33], v[0:1], v[0:1], v[62:63]
	s_nop 0
	v_pk_add_f32 v[32:33], v[34:35], v[32:33] op_sel_hi:[0,1]
	v_pk_fma_f32 v[32:33], v[2:3], v[2:3], v[32:33]
	v_mul_f32_e32 v34, v3, v3
	v_pk_add_f32 v[32:33], v[34:35], v[32:33] op_sel_hi:[0,1]
	v_pk_fma_f32 v[32:33], v[4:5], v[4:5], v[32:33]
	v_mul_f32_e32 v34, v5, v5
	v_pk_add_f32 v[32:33], v[34:35], v[32:33] op_sel_hi:[0,1]
	v_pk_fma_f32 v[32:33], v[6:7], v[6:7], v[32:33]
	v_mul_f32_e32 v34, v7, v7
	v_pk_add_f32 v[32:33], v[34:35], v[32:33] op_sel_hi:[0,1]
	v_pk_mul_f32 v[34:35], v[44:45], v[60:61] op_sel_hi:[1,0]
	s_nop 0
	v_pk_fma_f32 v[12:13], v[12:13], v[56:57], v[34:35] op_sel_hi:[1,0,1] neg_lo:[0,0,1] neg_hi:[0,0,1]
	v_pk_mul_f32 v[34:35], v[42:43], v[60:61] op_sel_hi:[1,0]
	s_nop 0
	v_pk_fma_f32 v[10:11], v[10:11], v[56:57], v[34:35] op_sel_hi:[1,0,1] neg_lo:[0,0,1] neg_hi:[0,0,1]
	v_pk_mul_f32 v[34:35], v[40:41], v[60:61] op_sel_hi:[1,0]
	s_nop 0
	v_pk_fma_f32 v[8:9], v[8:9], v[56:57], v[34:35] op_sel_hi:[1,0,1] neg_lo:[0,0,1] neg_hi:[0,0,1]
	s_nop 0
	v_pk_fma_f32 v[32:33], v[8:9], v[8:9], v[32:33]
	v_mul_f32_e32 v34, v9, v9
	v_pk_add_f32 v[32:33], v[34:35], v[32:33] op_sel_hi:[0,1]
	v_pk_fma_f32 v[32:33], v[10:11], v[10:11], v[32:33]
	v_mul_f32_e32 v34, v11, v11
	v_pk_add_f32 v[32:33], v[34:35], v[32:33] op_sel_hi:[0,1]
	v_pk_fma_f32 v[32:33], v[12:13], v[12:13], v[32:33]
	v_mul_f32_e32 v34, v13, v13
	v_pk_add_f32 v[32:33], v[34:35], v[32:33] op_sel_hi:[0,1]
	v_pk_fma_f32 v[32:33], v[14:15], v[14:15], v[32:33]
	v_mul_f32_e32 v34, v15, v15
	v_pk_add_f32 v[32:33], v[34:35], v[32:33] op_sel_hi:[0,1]
	v_mov_b32_e32 v33, v32
	s_nop 1
	v_permlane32_swap_b32_e32 v32, v33
	v_add_f32_e32 v32, v32, v33
	v_fmamk_f32 v32, v32, 0x3c800000, v245
	v_cmp_gt_f32_e32 vcc, s0, v32
	v_mul_f32_e32 v33, 0x4f800000, v32
	s_nop 0
	v_cndmask_b32_e32 v32, v32, v33, vcc
	v_sqrt_f32_e32 v33, v32
	s_nop 0
	v_add_u32_e32 v34, -1, v33
	v_fma_f32 v35, -v34, v33, v32
	v_cmp_ge_f32_e64 s[0:1], 0, v35
	v_add_u32_e32 v35, 1, v33
	s_nop 0
	v_cndmask_b32_e64 v34, v33, v34, s[0:1]
	v_fma_f32 v33, -v35, v33, v32
	v_cmp_lt_f32_e64 s[0:1], 0, v33
	s_nop 1
	v_cndmask_b32_e64 v33, v34, v35, s[0:1]
	v_mul_f32_e32 v34, 0x37800000, v33
	v_cndmask_b32_e32 v33, v33, v34, vcc
	v_cmp_class_f32_e32 vcc, v32, v250
	s_nop 1
	v_cndmask_b32_e32 v32, v33, v32, vcc
	v_div_scale_f32 v33, s[0:1], v32, v32, v61
	v_rcp_f32_e32 v34, v33
	s_mov_b32 s0, 0x1ad00000
	v_fma_f32 v35, -v33, v34, 1.0
	v_fmac_f32_e32 v34, v35, v34
	v_div_scale_f32 v35, vcc, v61, v32, v61
	v_mul_f32_e32 v36, v35, v34
	v_fma_f32 v37, -v33, v36, v35
	v_fmac_f32_e32 v36, v37, v34
	v_fma_f32 v33, -v33, v36, v35
	v_div_fmas_f32 v33, v33, v34, v36
	v_div_fixup_f32 v32, v33, v32, v61
	v_pk_mul_f32 v[16:17], v[16:17], v[32:33] op_sel_hi:[1,0]
	v_pk_mul_f32 v[18:19], v[18:19], v[32:33] op_sel_hi:[1,0]
	v_pk_mul_f32 v[16:17], v[144:145], v[16:17]
	v_pk_mul_f32 v[18:19], v[146:147], v[18:19]
	v_cvt_pk_bf16_f32 v16, v16, v17
	v_cvt_pk_bf16_f32 v17, v18, v19
	v_pk_mul_f32 v[18:19], v[20:21], v[32:33] op_sel_hi:[1,0]
	v_pk_mul_f32 v[20:21], v[22:23], v[32:33] op_sel_hi:[1,0]
	v_pk_mul_f32 v[18:19], v[148:149], v[18:19]
	v_pk_mul_f32 v[20:21], v[150:151], v[20:21]
	v_cvt_pk_bf16_f32 v18, v18, v19
	v_cvt_pk_bf16_f32 v19, v20, v21
	v_add_co_u32_e32 v20, vcc, s0, v58
	v_permlane32_swap_b32_e32 v16, v18
	v_permlane32_swap_b32_e32 v17, v19
	v_addc_co_u32_e32 v21, vcc, 0, v59, vcc
	global_store_dwordx4 v[20:21], v[16:19], off offset:1536
	v_pk_mul_f32 v[24:25], v[24:25], v[32:33] op_sel_hi:[1,0]
	v_pk_mul_f32 v[0:1], v[0:1], v[32:33] op_sel_hi:[1,0]
	v_pk_mul_f32 v[2:3], v[2:3], v[32:33] op_sel_hi:[1,0]
	v_pk_mul_f32 v[8:9], v[8:9], v[32:33] op_sel_hi:[1,0]
	v_pk_mul_f32 v[16:17], v[152:153], v[24:25]
	v_pk_mul_f32 v[24:25], v[26:27], v[32:33] op_sel_hi:[1,0]
	v_cvt_pk_bf16_f32 v16, v16, v17
	v_pk_mul_f32 v[18:19], v[154:155], v[24:25]
	s_nop 0
	v_cvt_pk_bf16_f32 v17, v18, v19
	v_pk_mul_f32 v[18:19], v[28:29], v[32:33] op_sel_hi:[1,0]
	v_pk_mul_f32 v[18:19], v[18:19], v[156:157]
	v_pk_mul_f32 v[20:21], v[30:31], v[32:33] op_sel_hi:[1,0]
	v_cvt_pk_bf16_f32 v18, v18, v19
	v_pk_mul_f32 v[20:21], v[20:21], v[158:159]
	s_nop 0
	v_permlane32_swap_b32_e32 v16, v18
	v_cvt_pk_bf16_f32 v19, v20, v21
	s_nop 1
	v_permlane32_swap_b32_e32 v17, v19
	global_store_dwordx4 v[54:55], v[16:19], off offset:32
	v_pk_mul_f32 v[0:1], v[0:1], v[160:161]
	v_pk_mul_f32 v[2:3], v[2:3], v[162:163]
	v_cvt_pk_bf16_f32 v0, v0, v1
	v_cvt_pk_bf16_f32 v1, v2, v3
	v_pk_mul_f32 v[2:3], v[4:5], v[32:33] op_sel_hi:[1,0]
	v_pk_mul_f32 v[4:5], v[6:7], v[32:33] op_sel_hi:[1,0]
	v_pk_mul_f32 v[2:3], v[2:3], v[164:165]
	v_pk_mul_f32 v[4:5], v[4:5], v[166:167]
	v_cvt_pk_bf16_f32 v2, v2, v3
	v_cvt_pk_bf16_f32 v3, v4, v5
	s_nop 0
	v_permlane32_swap_b32_e32 v0, v2
	v_permlane32_swap_b32_e32 v1, v3
	global_store_dwordx4 v[54:55], v[0:3], off offset:64
	s_nop 1
	v_pk_mul_f32 v[0:1], v[8:9], v[168:169]
	v_pk_mul_f32 v[8:9], v[10:11], v[32:33] op_sel_hi:[1,0]
	v_cvt_pk_bf16_f32 v0, v0, v1
	v_pk_mul_f32 v[2:3], v[8:9], v[170:171]
	s_nop 0
	v_cvt_pk_bf16_f32 v1, v2, v3
	v_pk_mul_f32 v[2:3], v[12:13], v[32:33] op_sel_hi:[1,0]
	v_pk_mul_f32 v[2:3], v[2:3], v[172:173]
	v_pk_mul_f32 v[4:5], v[14:15], v[32:33] op_sel_hi:[1,0]
	v_cvt_pk_bf16_f32 v2, v2, v3
	v_pk_mul_f32 v[4:5], v[4:5], v[174:175]
	s_nop 0
	v_permlane32_swap_b32_e32 v0, v2
	v_cvt_pk_bf16_f32 v3, v4, v5
	s_nop 1
	v_permlane32_swap_b32_e32 v1, v3
	global_store_dwordx4 v[54:55], v[0:3], off offset:96
	s_cbranch_scc1 .LBB0_743
